# attention tile loop: after the tile barrier the first sub-tile's LDS reads are requested before the next tile's K/V global loads
# baseline (speedup 1.0000x reference)
; #define LAS __attribute__((address_space(3)))
; __device__ __forceinline__ void dattn_unit(LAS unsigned char* lds, int b, int h, int qb, const bf16* Q, const bf16* K, const bf16* V, bf16* YB, float lam, const float* subg, float oml, int tid) {
;     ...
;     for (int t = 0; t < NT; ++t) {
;         if (t + 1 < NT) { const size_t adv = (size_t)(t + 1) * 64 * 1024; kr0 = *(const v4u*)(kg + adv); kr1 = *(const v4u*)(kg + adv + 64); vr0 = *(const v4u*)(vg + adv); vr1 = *(const v4u*)(vg + adv + 8); }
;         const LAS bf16* Ks = (const LAS bf16*)(lds + (t & 1) * AT_BUF + AT_KS); const LAS bf16* Vt = (const LAS bf16*)(lds + (t & 1) * AT_BUF + AT_VT);
;         const int kvbase = t * 64;
;         if (kvbase <= qmax) {
.Lskip_tile:
	v_lshl_add_u64 v[128:129], v[184:185], 0, s[98:99]
	v_lshl_add_u64 v[130:131], v[182:183], 0, s[100:101]
	global_load_dwordx4 v[168:171], v[128:129], off
	global_load_dwordx4 v[172:175], v[128:129], off offset:128
	global_load_dwordx4 v[164:167], v[130:131], off
	global_load_dwordx4 v[160:163], v[130:131], off offset:16
	s_branch .LBB0_226

; #define LAS __attribute__((address_space(3)))
; __device__ __forceinline__ void dattn_unit(LAS unsigned char* lds, int b, int h, int qb, const bf16* Q, const bf16* K, const bf16* V, bf16* YB, float lam, const float* subg, float oml, int tid) {
;     ...
;     for (int t = 0; t < NT; ++t) {
;         if (t + 1 < NT) { const size_t adv = (size_t)(t + 1) * 64 * 1024; kr0 = *(const v4u*)(kg + adv); kr1 = *(const v4u*)(kg + adv + 64); vr0 = *(const v4u*)(vg + adv); vr1 = *(const v4u*)(vg + adv + 8); }
;         const LAS bf16* Ks = (const LAS bf16*)(lds + (t & 1) * AT_BUF + AT_KS); const LAS bf16* Vt = (const LAS bf16*)(lds + (t & 1) * AT_BUF + AT_VT);
;         const int kvbase = t * 64;
;         if (kvbase <= qmax) {
;     ...
; #pragma unroll
;         for (int sub = 0; sub < 2; ++sub) {
;             if (kvbase + 32 * sub > qmax) continue;
;             const bool need_bm = kvbase + 32 * sub + 31 + 113 > qmin;
;             LAS bf16x8* qsp = qs; asm volatile("" : "+v"(qsp));
;             f32x16 s0, s1;
; #pragma unroll
;             for (int r = 0; r < 16; ++r) { s0[r] = -mref[0]; s1[r] = -mref[1]; }
;             {
;                 const LAS bf16* kp = Ks + (32 * sub + ql) * 72 + hi * 8;
;                 bf16x8 ka = *(const LAS bf16x8*)kp, kb = *(const LAS bf16x8*)(kp + 64 * 72), qa = qsp[0], qb = qsp[4 * 64];
;                 __builtin_amdgcn_sched_group_barrier(0x100, 4, 0);
; #pragma unroll
;                 for (int ks = 0; ks < 4; ++ks) { bf16x8 ka2 = ka, kb2 = kb, qa2 = qa, qb2 = qb;
;                     if (ks < 3) { ka2 = *(const LAS bf16x8*)(kp + (ks + 1) * 16); kb2 = *(const LAS bf16x8*)(kp + 64 * 72 + (ks + 1) * 16); qa2 = qsp[(ks + 1) * 64]; qb2 = qsp[(4 + ks + 1) * 64];
;                         __builtin_amdgcn_sched_group_barrier(0x100, 4, 0); }
;                     s0 = __builtin_amdgcn_mfma_f32_32x32x16_bf16(ka, qa, s0, 0, 0, 0);
;                     s1 = __builtin_amdgcn_mfma_f32_32x32x16_bf16(kb, qb, s1, 0, 0, 0);
;                     __builtin_amdgcn_sched_group_barrier(0x008, 2, 0);
;                     ka = ka2; kb = kb2; qa = qa2; qb = qb2; }
;             }
.LBB0_227:
	s_add_i32 s18, s58, 0xffffff50
	s_cmp_gt_i32 s18, s35
	s_cbranch_scc1 .Lskip_tile
	s_bitcmp1_b32 s59, 0
	s_cselect_b32 s18, 0x9000, 0
	s_add_i32 s38, s18, 0
	v_add3_u32 v199, s38, v208, v192
	ds_read_b128 v[138:141], v199
	ds_read_b128 v[200:203], v199 offset:9216
	ds_read_b128 v[204:207], v189
	ds_read_b128 v[218:221], v189 offset:4096
	ds_read_b128 v[222:225], v199 offset:32
	ds_read_b128 v[226:229], v199 offset:9248
	ds_read_b128 v[230:233], v189 offset:1024
	ds_read_b128 v[234:237], v189 offset:5120
	v_lshl_add_u64 v[128:129], v[184:185], 0, s[98:99]
	v_lshl_add_u64 v[130:131], v[182:183], 0, s[100:101]
	global_load_dwordx4 v[168:171], v[128:129], off
	global_load_dwordx4 v[172:175], v[128:129], off offset:128
	global_load_dwordx4 v[164:167], v[130:131], off
	global_load_dwordx4 v[160:163], v[130:131], off offset:16
	v_xor_b32_e32 v144, 0x80000000, v190
	v_xor_b32_e32 v128, 0x80000000, v191
	v_mov_b32_e32 v145, v144
	v_mov_b64_e32 v[146:147], v[144:145]
	v_mov_b64_e32 v[148:149], v[144:145]
	v_mov_b64_e32 v[150:151], v[144:145]
	v_mov_b64_e32 v[152:153], v[144:145]
	v_mov_b64_e32 v[154:155], v[144:145]
	v_mov_b64_e32 v[156:157], v[144:145]
	v_mov_b64_e32 v[158:159], v[144:145]
	v_mov_b32_e32 v129, v128
	v_mov_b64_e32 v[130:131], v[128:129]
	v_mov_b64_e32 v[132:133], v[128:129]
	v_mov_b64_e32 v[134:135], v[128:129]
	v_mov_b64_e32 v[136:137], v[128:129]
	s_waitcnt lgkmcnt(5)
	v_mfma_f32_32x32x16_bf16 v[144:159], v[138:141], v[204:207], v[144:159]
	v_mov_b64_e32 v[142:143], v[128:129]
	v_mov_b64_e32 v[138:139], v[128:129]
	v_mov_b64_e32 v[140:141], v[128:129]
	s_sub_i32 s18, s58, 32
	s_cmp_le_i32 s18, s31
	s_waitcnt lgkmcnt(4)
	v_mfma_f32_32x32x16_bf16 v[128:143], v[200:203], v[218:221], v[128:143]
	ds_read_b128 v[200:203], v199 offset:64
	ds_read_b128 v[204:207], v199 offset:9280
	ds_read_b128 v[218:221], v189 offset:2048
	ds_read_b128 v[238:241], v189 offset:6144
	s_waitcnt lgkmcnt(5)
	v_mfma_f32_32x32x16_bf16 v[144:159], v[222:225], v[230:233], v[144:159]
	s_waitcnt lgkmcnt(4)
	v_mfma_f32_32x32x16_bf16 v[128:143], v[226:229], v[234:237], v[128:143]
	ds_read_b128 v[222:225], v199 offset:96
	ds_read_b128 v[226:229], v199 offset:9312
	ds_read_b128 v[230:233], v189 offset:3072
	ds_read_b128 v[234:237], v189 offset:7168
	s_waitcnt lgkmcnt(5)
	v_mfma_f32_32x32x16_bf16 v[144:159], v[200:203], v[218:221], v[144:159]
	s_cbranch_scc0 .Lqk_diag0
	s_waitcnt lgkmcnt(1)
	v_mfma_f32_32x32x16_bf16 v[144:159], v[222:225], v[230:233], v[144:159]
	v_add3_u32 v219, s38, v193, v192
	ds_read_b128 v[212:215], v219 offset:32256
	ds_read_b128 v[220:223], v219 offset:18432
	v_mfma_f32_32x32x16_bf16 v[128:143], v[204:207], v[238:241], v[128:143]
	s_waitcnt lgkmcnt(2)
	v_mfma_f32_32x32x16_bf16 v[128:143], v[226:229], v[234:237], v[128:143]
	ds_read_b128 v[228:231], v219 offset:23040
	ds_read_b128 v[232:235], v219 offset:23072
	ds_read_b128 v[236:239], v219 offset:27648
	ds_read_b128 v[240:243], v219 offset:27680
	s_nop 1
